# grid barrier: waiting workgroups issue the acquire's L1 invalidate before polling (L1 stays empty while parked), off the release-to-restart path
# speedup vs baseline: 1.0690x; 1.0147x over previous
; __device__ __forceinline__ unsigned xb_ld(unsigned* p)              { return __hip_atomic_load(p, __ATOMIC_RELAXED, __HIP_MEMORY_SCOPE_AGENT); }
; #define XB_SPIN(cond, bar) do { unsigned _sp = 0; while (cond) { __builtin_amdgcn_s_sleep(1); \
;     if ((++_sp & 255u) == 0u) { if (xb_ld(&(bar)[XB_TMO])) break; if (_sp > XB_SPIN_CAP) { atomicAdd(&(bar)[XB_TMO], 1u); break; } } } } while (0)
; __device__ __forceinline__ void xcd_barrier(const XcdBarrier& b) {
;     ...
;         } else {
;             XB_SPIN(xb_ld(&bar[XB_XGEN(b.x)]) == gen, bar);
;             __builtin_amdgcn_fence(__ATOMIC_ACQUIRE, "agent");
;             asm volatile("s_waitcnt vmcnt(0)" ::: "memory");
.LBB0_71:
	s_or_b64 exec, exec, s[10:11]
	v_cvt_f32_u32_e32 v4, v2
	s_waitcnt vmcnt(0)
	v_readfirstlane_b32 s2, v3
	v_sub_u32_e32 v3, 0, v2
	v_rcp_iflag_f32_e32 v4, v4
	v_add_u32_e32 v5, s2, v1
	v_mul_f32_e32 v4, 0x4f7ffffe, v4
	v_cvt_u32_f32_e32 v4, v4
	v_mul_lo_u32 v1, v3, v4
	v_mul_hi_u32 v1, v4, v1
	v_add_u32_e32 v1, v4, v1
	v_mul_hi_u32 v1, v5, v1
	v_mul_lo_u32 v3, v1, v2
	v_sub_u32_e32 v3, v5, v3
	v_add_u32_e32 v4, 1, v1
	v_cmp_ge_u32_e32 vcc, v3, v2
	s_nop 1
	v_cndmask_b32_e32 v1, v1, v4, vcc
	v_sub_u32_e32 v4, v3, v2
	v_cndmask_b32_e32 v3, v3, v4, vcc
	v_add_u32_e32 v4, 1, v1
	v_cmp_ge_u32_e32 vcc, v3, v2
	v_add_u32_e32 v3, 1, v5
	s_nop 0
	v_cndmask_b32_e32 v1, v1, v4, vcc
	v_mul_lo_u32 v4, v2, v1
	v_add_u32_e32 v2, v4, v2
	v_cmp_ne_u32_e32 vcc, v3, v2
	s_and_saveexec_b64 s[6:7], vcc
	s_xor_b64 s[6:7], exec, s[6:7]
	s_cbranch_execz .LBB0_85
	s_waitcnt lgkmcnt(0)
	buffer_inv sc1
	v_mov_b32_e32 v0, 0x2000
	global_load_dword v0, v0, s[4:5] offset:1024 sc1
	s_add_u32 s16, s4, 0x2400
	s_addc_u32 s17, s5, 0
	s_waitcnt vmcnt(0)
	v_cmp_eq_u32_e32 vcc, v0, v1
	s_and_saveexec_b64 s[10:11], vcc
	s_cbranch_execz .LBB0_84
	s_add_u32 s12, s34, 0x101200
	s_addc_u32 s13, s35, 0
	s_mov_b32 s2, 1
	s_mov_b64 s[18:19], 0
	v_mov_b32_e32 v0, 0
	s_branch .LBB0_75

; __device__ __forceinline__ unsigned xb_ld(unsigned* p)              { return __hip_atomic_load(p, __ATOMIC_RELAXED, __HIP_MEMORY_SCOPE_AGENT); }
; #define XB_SPIN(cond, bar) do { unsigned _sp = 0; while (cond) { __builtin_amdgcn_s_sleep(1); \
;     if ((++_sp & 255u) == 0u) { if (xb_ld(&(bar)[XB_TMO])) break; if (_sp > XB_SPIN_CAP) { atomicAdd(&(bar)[XB_TMO], 1u); break; } } } } while (0)
; __device__ __forceinline__ void xcd_barrier(const XcdBarrier& b) {
;     ...
;             XB_SPIN(xb_ld(&bar[XB_XGEN(b.x)]) == gen, bar);
;             __builtin_amdgcn_fence(__ATOMIC_ACQUIRE, "agent");
;             asm volatile("s_waitcnt vmcnt(0)" ::: "memory");
.LBB0_84:
	s_or_b64 exec, exec, s[10:11]
	s_waitcnt vmcnt(0)
	s_waitcnt vmcnt(0)

; __device__ __forceinline__ unsigned xb_ld(unsigned* p)              { return __hip_atomic_load(p, __ATOMIC_RELAXED, __HIP_MEMORY_SCOPE_AGENT); }
; #define XB_SPIN(cond, bar) do { unsigned _sp = 0; while (cond) { __builtin_amdgcn_s_sleep(1); \
;     if ((++_sp & 255u) == 0u) { if (xb_ld(&(bar)[XB_TMO])) break; if (_sp > XB_SPIN_CAP) { atomicAdd(&(bar)[XB_TMO], 1u); break; } } } } while (0)
; __device__ __forceinline__ void xcd_barrier(const XcdBarrier& b) {
;     ...
;         } else {
;             XB_SPIN(xb_ld(&bar[XB_XGEN(b.x)]) == gen, bar);
;             __builtin_amdgcn_fence(__ATOMIC_ACQUIRE, "agent");
;             asm volatile("s_waitcnt vmcnt(0)" ::: "memory");
.LBB0_197:
	s_or_b64 exec, exec, s[8:9]
	v_cvt_f32_u32_e32 v4, v2
	s_waitcnt vmcnt(0)
	v_readfirstlane_b32 s6, v3
	v_sub_u32_e32 v3, 0, v2
	v_rcp_iflag_f32_e32 v4, v4
	v_add_u32_e32 v5, s6, v1
	v_mul_f32_e32 v4, 0x4f7ffffe, v4
	v_cvt_u32_f32_e32 v4, v4
	v_mul_lo_u32 v1, v3, v4
	v_mul_hi_u32 v1, v4, v1
	v_add_u32_e32 v1, v4, v1
	v_mul_hi_u32 v1, v5, v1
	v_mul_lo_u32 v3, v1, v2
	v_sub_u32_e32 v3, v5, v3
	v_add_u32_e32 v4, 1, v1
	v_cmp_ge_u32_e32 vcc, v3, v2
	s_nop 1
	v_cndmask_b32_e32 v1, v1, v4, vcc
	v_sub_u32_e32 v4, v3, v2
	v_cndmask_b32_e32 v3, v3, v4, vcc
	v_add_u32_e32 v4, 1, v1
	v_cmp_ge_u32_e32 vcc, v3, v2
	v_add_u32_e32 v3, 1, v5
	s_nop 0
	v_cndmask_b32_e32 v1, v1, v4, vcc
	v_mul_lo_u32 v4, v2, v1
	v_add_u32_e32 v2, v4, v2
	v_cmp_ne_u32_e32 vcc, v3, v2
	s_and_saveexec_b64 s[6:7], vcc
	s_xor_b64 s[6:7], exec, s[6:7]
	s_cbranch_execz .LBB0_211
	s_waitcnt lgkmcnt(0)
	buffer_inv sc1
	v_mov_b32_e32 v0, 0x2000
	global_load_dword v0, v0, s[4:5] offset:1024 sc1
	s_add_u32 s12, s4, 0x2400
	s_addc_u32 s13, s5, 0
	s_waitcnt vmcnt(0)
	v_cmp_eq_u32_e32 vcc, v0, v1
	s_and_saveexec_b64 s[8:9], vcc
	s_cbranch_execz .LBB0_210
	s_add_u32 s10, s34, 0x101200
	s_addc_u32 s11, s35, 0
	s_mov_b32 s15, 1
	s_mov_b64 s[16:17], 0
	v_mov_b32_e32 v0, 0
	s_branch .LBB0_201

; __device__ __forceinline__ unsigned xb_ld(unsigned* p)              { return __hip_atomic_load(p, __ATOMIC_RELAXED, __HIP_MEMORY_SCOPE_AGENT); }
; #define XB_SPIN(cond, bar) do { unsigned _sp = 0; while (cond) { __builtin_amdgcn_s_sleep(1); \
;     if ((++_sp & 255u) == 0u) { if (xb_ld(&(bar)[XB_TMO])) break; if (_sp > XB_SPIN_CAP) { atomicAdd(&(bar)[XB_TMO], 1u); break; } } } } while (0)
; __device__ __forceinline__ void xcd_barrier(const XcdBarrier& b) {
;     ...
;             XB_SPIN(xb_ld(&bar[XB_XGEN(b.x)]) == gen, bar);
;             __builtin_amdgcn_fence(__ATOMIC_ACQUIRE, "agent");
;             asm volatile("s_waitcnt vmcnt(0)" ::: "memory");
.LBB0_210:
	s_or_b64 exec, exec, s[8:9]
	s_waitcnt vmcnt(0)
	s_waitcnt vmcnt(0)

; __device__ __forceinline__ unsigned xb_ld(unsigned* p)              { return __hip_atomic_load(p, __ATOMIC_RELAXED, __HIP_MEMORY_SCOPE_AGENT); }
; #define XB_SPIN(cond, bar) do { unsigned _sp = 0; while (cond) { __builtin_amdgcn_s_sleep(1); \
;     if ((++_sp & 255u) == 0u) { if (xb_ld(&(bar)[XB_TMO])) break; if (_sp > XB_SPIN_CAP) { atomicAdd(&(bar)[XB_TMO], 1u); break; } } } } while (0)
; __device__ __forceinline__ void xcd_barrier(const XcdBarrier& b) {
;     ...
;         } else {
;             XB_SPIN(xb_ld(&bar[XB_XGEN(b.x)]) == gen, bar);
;             __builtin_amdgcn_fence(__ATOMIC_ACQUIRE, "agent");
;             asm volatile("s_waitcnt vmcnt(0)" ::: "memory");
.LBB0_417:
	s_or_b64 exec, exec, s[10:11]
	v_cvt_f32_u32_e32 v4, v2
	s_waitcnt vmcnt(0)
	v_readfirstlane_b32 s6, v3
	v_sub_u32_e32 v3, 0, v2
	v_rcp_iflag_f32_e32 v4, v4
	v_add_u32_e32 v5, s6, v1
	v_mul_f32_e32 v4, 0x4f7ffffe, v4
	v_cvt_u32_f32_e32 v4, v4
	v_mul_lo_u32 v1, v3, v4
	v_mul_hi_u32 v1, v4, v1
	v_add_u32_e32 v1, v4, v1
	v_mul_hi_u32 v1, v5, v1
	v_mul_lo_u32 v3, v1, v2
	v_sub_u32_e32 v3, v5, v3
	v_add_u32_e32 v4, 1, v1
	v_cmp_ge_u32_e32 vcc, v3, v2
	s_nop 1
	v_cndmask_b32_e32 v1, v1, v4, vcc
	v_sub_u32_e32 v4, v3, v2
	v_cndmask_b32_e32 v3, v3, v4, vcc
	v_add_u32_e32 v4, 1, v1
	v_cmp_ge_u32_e32 vcc, v3, v2
	v_add_u32_e32 v3, 1, v5
	s_nop 0
	v_cndmask_b32_e32 v1, v1, v4, vcc
	v_mul_lo_u32 v4, v2, v1
	v_add_u32_e32 v2, v4, v2
	v_cmp_ne_u32_e32 vcc, v3, v2
	s_and_saveexec_b64 s[6:7], vcc
	s_xor_b64 s[6:7], exec, s[6:7]
	s_cbranch_execz .LBB0_431
	s_waitcnt lgkmcnt(0)
	buffer_inv sc1
	v_mov_b32_e32 v0, 0x2000
	global_load_dword v0, v0, s[4:5] offset:1024 sc1
	s_add_u32 s16, s4, 0x2400
	s_addc_u32 s17, s5, 0
	s_waitcnt vmcnt(0)
	v_cmp_eq_u32_e32 vcc, v0, v1
	s_and_saveexec_b64 s[10:11], vcc
	s_cbranch_execz .LBB0_430
	s_add_u32 s12, s34, 0x101200
	s_addc_u32 s13, s35, 0
	s_mov_b32 s33, 1
	s_mov_b64 s[18:19], 0
	v_mov_b32_e32 v0, 0
	s_branch .LBB0_421

; __device__ __forceinline__ unsigned xb_ld(unsigned* p)              { return __hip_atomic_load(p, __ATOMIC_RELAXED, __HIP_MEMORY_SCOPE_AGENT); }
; #define XB_SPIN(cond, bar) do { unsigned _sp = 0; while (cond) { __builtin_amdgcn_s_sleep(1); \
;     if ((++_sp & 255u) == 0u) { if (xb_ld(&(bar)[XB_TMO])) break; if (_sp > XB_SPIN_CAP) { atomicAdd(&(bar)[XB_TMO], 1u); break; } } } } while (0)
; __device__ __forceinline__ void xcd_barrier(const XcdBarrier& b) {
;     ...
;         } else {
;             XB_SPIN(xb_ld(&bar[XB_XGEN(b.x)]) == gen, bar);
;             __builtin_amdgcn_fence(__ATOMIC_ACQUIRE, "agent");
;             asm volatile("s_waitcnt vmcnt(0)" ::: "memory");
.LBB0_931:
	s_or_b64 exec, exec, s[8:9]
	v_cvt_f32_u32_e32 v4, v2
	s_waitcnt vmcnt(0)
	v_readfirstlane_b32 s2, v3
	v_sub_u32_e32 v3, 0, v2
	v_rcp_iflag_f32_e32 v4, v4
	v_add_u32_e32 v5, s2, v1
	v_mul_f32_e32 v4, 0x4f7ffffe, v4
	v_cvt_u32_f32_e32 v4, v4
	v_mul_lo_u32 v1, v3, v4
	v_mul_hi_u32 v1, v4, v1
	v_add_u32_e32 v1, v4, v1
	v_mul_hi_u32 v1, v5, v1
	v_mul_lo_u32 v3, v1, v2
	v_sub_u32_e32 v3, v5, v3
	v_add_u32_e32 v4, 1, v1
	v_cmp_ge_u32_e32 vcc, v3, v2
	s_nop 1
	v_cndmask_b32_e32 v1, v1, v4, vcc
	v_sub_u32_e32 v4, v3, v2
	v_cndmask_b32_e32 v3, v3, v4, vcc
	v_add_u32_e32 v4, 1, v1
	v_cmp_ge_u32_e32 vcc, v3, v2
	v_add_u32_e32 v3, 1, v5
	s_nop 0
	v_cndmask_b32_e32 v1, v1, v4, vcc
	v_mul_lo_u32 v4, v2, v1
	v_add_u32_e32 v2, v4, v2
	v_cmp_ne_u32_e32 vcc, v3, v2
	s_and_saveexec_b64 s[6:7], vcc
	s_xor_b64 s[6:7], exec, s[6:7]
	s_cbranch_execz .LBB0_945
	s_waitcnt lgkmcnt(0)
	buffer_inv sc1
	v_mov_b32_e32 v0, 0x2000
	global_load_dword v0, v0, s[4:5] offset:1024 sc1
	s_add_u32 s12, s4, 0x2400
	s_addc_u32 s13, s5, 0
	s_waitcnt vmcnt(0)
	v_cmp_eq_u32_e32 vcc, v0, v1
	s_and_saveexec_b64 s[8:9], vcc
	s_cbranch_execz .LBB0_944
	s_add_u32 s10, s34, 0x101200
	s_addc_u32 s11, s35, 0
	s_mov_b32 s2, 1
	s_mov_b64 s[16:17], 0
	v_mov_b32_e32 v0, 0
	s_branch .LBB0_935

; __device__ __forceinline__ unsigned xb_ld(unsigned* p)              { return __hip_atomic_load(p, __ATOMIC_RELAXED, __HIP_MEMORY_SCOPE_AGENT); }
; #define XB_SPIN(cond, bar) do { unsigned _sp = 0; while (cond) { __builtin_amdgcn_s_sleep(1); \
;     if ((++_sp & 255u) == 0u) { if (xb_ld(&(bar)[XB_TMO])) break; if (_sp > XB_SPIN_CAP) { atomicAdd(&(bar)[XB_TMO], 1u); break; } } } } while (0)
; __device__ __forceinline__ void xcd_barrier(const XcdBarrier& b) {
;     ...
;         } else {
;             XB_SPIN(xb_ld(&bar[XB_XGEN(b.x)]) == gen, bar);
;             __builtin_amdgcn_fence(__ATOMIC_ACQUIRE, "agent");
;             asm volatile("s_waitcnt vmcnt(0)" ::: "memory");
.LBB0_1747:
	s_or_b64 exec, exec, s[8:9]
	v_cvt_f32_u32_e32 v4, v2
	s_waitcnt vmcnt(0)
	v_readfirstlane_b32 s6, v3
	v_sub_u32_e32 v3, 0, v2
	v_rcp_iflag_f32_e32 v4, v4
	v_add_u32_e32 v5, s6, v1
	v_mul_f32_e32 v4, 0x4f7ffffe, v4
	v_cvt_u32_f32_e32 v4, v4
	v_mul_lo_u32 v1, v3, v4
	v_mul_hi_u32 v1, v4, v1
	v_add_u32_e32 v1, v4, v1
	v_mul_hi_u32 v1, v5, v1
	v_mul_lo_u32 v3, v1, v2
	v_sub_u32_e32 v3, v5, v3
	v_add_u32_e32 v4, 1, v1
	v_cmp_ge_u32_e32 vcc, v3, v2
	s_nop 1
	v_cndmask_b32_e32 v1, v1, v4, vcc
	v_sub_u32_e32 v4, v3, v2
	v_cndmask_b32_e32 v3, v3, v4, vcc
	v_add_u32_e32 v4, 1, v1
	v_cmp_ge_u32_e32 vcc, v3, v2
	v_add_u32_e32 v3, 1, v5
	s_nop 0
	v_cndmask_b32_e32 v1, v1, v4, vcc
	v_mul_lo_u32 v4, v2, v1
	v_add_u32_e32 v2, v4, v2
	v_cmp_ne_u32_e32 vcc, v3, v2
	s_and_saveexec_b64 s[6:7], vcc
	s_xor_b64 s[6:7], exec, s[6:7]
	s_cbranch_execz .LBB0_1761
	s_waitcnt lgkmcnt(0)
	buffer_inv sc1
	v_mov_b32_e32 v0, 0x2000
	global_load_dword v0, v0, s[4:5] offset:1024 sc1
	s_add_u32 s12, s4, 0x2400
	s_addc_u32 s13, s5, 0
	s_waitcnt vmcnt(0)
	v_cmp_eq_u32_e32 vcc, v0, v1
	s_and_saveexec_b64 s[8:9], vcc
	s_cbranch_execz .LBB0_1760
	s_add_u32 s10, s34, 0x101200
	s_addc_u32 s11, s35, 0
	s_mov_b32 s24, 1
	s_mov_b64 s[14:15], 0
	v_mov_b32_e32 v0, 0
	s_branch .LBB0_1751

; __device__ __forceinline__ unsigned xb_ld(unsigned* p)              { return __hip_atomic_load(p, __ATOMIC_RELAXED, __HIP_MEMORY_SCOPE_AGENT); }
; #define XB_SPIN(cond, bar) do { unsigned _sp = 0; while (cond) { __builtin_amdgcn_s_sleep(1); \
;     if ((++_sp & 255u) == 0u) { if (xb_ld(&(bar)[XB_TMO])) break; if (_sp > XB_SPIN_CAP) { atomicAdd(&(bar)[XB_TMO], 1u); break; } } } } while (0)
; __device__ __forceinline__ void xcd_barrier(const XcdBarrier& b) {
;     ...
;         } else {
;             XB_SPIN(xb_ld(&bar[XB_XGEN(b.x)]) == gen, bar);
;             __builtin_amdgcn_fence(__ATOMIC_ACQUIRE, "agent");
;             asm volatile("s_waitcnt vmcnt(0)" ::: "memory");
.LBB0_2006:
	s_or_b64 exec, exec, s[8:9]
	v_cvt_f32_u32_e32 v4, v2
	s_waitcnt vmcnt(0)
	v_readfirstlane_b32 s2, v3
	v_sub_u32_e32 v3, 0, v2
	v_rcp_iflag_f32_e32 v4, v4
	v_add_u32_e32 v5, s2, v1
	v_mul_f32_e32 v4, 0x4f7ffffe, v4
	v_cvt_u32_f32_e32 v4, v4
	v_mul_lo_u32 v1, v3, v4
	v_mul_hi_u32 v1, v4, v1
	v_add_u32_e32 v1, v4, v1
	v_mul_hi_u32 v1, v5, v1
	v_mul_lo_u32 v3, v1, v2
	v_sub_u32_e32 v3, v5, v3
	v_add_u32_e32 v4, 1, v1
	v_cmp_ge_u32_e32 vcc, v3, v2
	s_nop 1
	v_cndmask_b32_e32 v1, v1, v4, vcc
	v_sub_u32_e32 v4, v3, v2
	v_cndmask_b32_e32 v3, v3, v4, vcc
	v_add_u32_e32 v4, 1, v1
	v_cmp_ge_u32_e32 vcc, v3, v2
	v_add_u32_e32 v3, 1, v5
	s_nop 0
	v_cndmask_b32_e32 v1, v1, v4, vcc
	v_mul_lo_u32 v4, v2, v1
	v_add_u32_e32 v2, v4, v2
	v_cmp_ne_u32_e32 vcc, v3, v2
	s_and_saveexec_b64 s[6:7], vcc
	s_xor_b64 s[6:7], exec, s[6:7]
	s_cbranch_execz .LBB0_2020
	s_waitcnt lgkmcnt(0)
	buffer_inv sc1
	v_mov_b32_e32 v0, 0x2000
	global_load_dword v0, v0, s[4:5] offset:1024 sc1
	s_add_u32 s12, s4, 0x2400
	s_addc_u32 s13, s5, 0
	s_waitcnt vmcnt(0)
	v_cmp_eq_u32_e32 vcc, v0, v1
	s_and_saveexec_b64 s[8:9], vcc
	s_cbranch_execz .LBB0_2019
	s_add_u32 s10, s34, 0x101200
	s_addc_u32 s11, s35, 0
	s_mov_b32 s2, 1
	s_mov_b64 s[14:15], 0
	v_mov_b32_e32 v0, 0
	s_branch .LBB0_2010

; __device__ __forceinline__ unsigned xb_ld(unsigned* p)              { return __hip_atomic_load(p, __ATOMIC_RELAXED, __HIP_MEMORY_SCOPE_AGENT); }
; #define XB_SPIN(cond, bar) do { unsigned _sp = 0; while (cond) { __builtin_amdgcn_s_sleep(1); \
;     if ((++_sp & 255u) == 0u) { if (xb_ld(&(bar)[XB_TMO])) break; if (_sp > XB_SPIN_CAP) { atomicAdd(&(bar)[XB_TMO], 1u); break; } } } } while (0)
; __device__ __forceinline__ void xcd_barrier(const XcdBarrier& b) {
;     ...
;         } else {
;             XB_SPIN(xb_ld(&bar[XB_XGEN(b.x)]) == gen, bar);
;             __builtin_amdgcn_fence(__ATOMIC_ACQUIRE, "agent");
;             asm volatile("s_waitcnt vmcnt(0)" ::: "memory");
.LBB0_2226:
	s_or_b64 exec, exec, s[10:11]
	v_cvt_f32_u32_e32 v4, v2
	s_waitcnt vmcnt(0)
	v_readfirstlane_b32 s2, v3
	v_sub_u32_e32 v3, 0, v2
	v_rcp_iflag_f32_e32 v4, v4
	v_add_u32_e32 v5, s2, v1
	v_mul_f32_e32 v4, 0x4f7ffffe, v4
	v_cvt_u32_f32_e32 v4, v4
	v_mul_lo_u32 v1, v3, v4
	v_mul_hi_u32 v1, v4, v1
	v_add_u32_e32 v1, v4, v1
	v_mul_hi_u32 v1, v5, v1
	v_mul_lo_u32 v3, v1, v2
	v_sub_u32_e32 v3, v5, v3
	v_add_u32_e32 v4, 1, v1
	v_cmp_ge_u32_e32 vcc, v3, v2
	s_nop 1
	v_cndmask_b32_e32 v1, v1, v4, vcc
	v_sub_u32_e32 v4, v3, v2
	v_cndmask_b32_e32 v3, v3, v4, vcc
	v_add_u32_e32 v4, 1, v1
	v_cmp_ge_u32_e32 vcc, v3, v2
	v_add_u32_e32 v3, 1, v5
	s_nop 0
	v_cndmask_b32_e32 v1, v1, v4, vcc
	v_mul_lo_u32 v4, v2, v1
	v_add_u32_e32 v2, v4, v2
	v_cmp_ne_u32_e32 vcc, v3, v2
	s_and_saveexec_b64 s[6:7], vcc
	s_xor_b64 s[6:7], exec, s[6:7]
	s_cbranch_execz .LBB0_2240
	s_waitcnt lgkmcnt(0)
	buffer_inv sc1
	v_mov_b32_e32 v0, 0x2000
	global_load_dword v0, v0, s[4:5] offset:1024 sc1
	s_add_u32 s14, s4, 0x2400
	s_addc_u32 s15, s5, 0
	s_waitcnt vmcnt(0)
	v_cmp_eq_u32_e32 vcc, v0, v1
	s_and_saveexec_b64 s[10:11], vcc
	s_cbranch_execz .LBB0_2239
	s_add_u32 s12, s34, 0x101200
	s_addc_u32 s13, s35, 0
	s_mov_b32 s2, 1
	s_mov_b64 s[16:17], 0
	v_mov_b32_e32 v0, 0
	s_branch .LBB0_2230

; __device__ __forceinline__ unsigned xb_ld(unsigned* p)              { return __hip_atomic_load(p, __ATOMIC_RELAXED, __HIP_MEMORY_SCOPE_AGENT); }
; #define XB_SPIN(cond, bar) do { unsigned _sp = 0; while (cond) { __builtin_amdgcn_s_sleep(1); \
;     if ((++_sp & 255u) == 0u) { if (xb_ld(&(bar)[XB_TMO])) break; if (_sp > XB_SPIN_CAP) { atomicAdd(&(bar)[XB_TMO], 1u); break; } } } } while (0)
; __device__ __forceinline__ void xcd_barrier(const XcdBarrier& b) {
;     ...
;         } else {
;             XB_SPIN(xb_ld(&bar[XB_XGEN(b.x)]) == gen, bar);
;             __builtin_amdgcn_fence(__ATOMIC_ACQUIRE, "agent");
;             asm volatile("s_waitcnt vmcnt(0)" ::: "memory");
.LBB0_2532:
	s_or_b64 exec, exec, s[6:7]
	v_cvt_f32_u32_e32 v4, v2
	s_waitcnt vmcnt(0)
	v_readfirstlane_b32 s4, v3
	v_sub_u32_e32 v3, 0, v2
	v_rcp_iflag_f32_e32 v4, v4
	v_add_u32_e32 v5, s4, v1
	v_mul_f32_e32 v4, 0x4f7ffffe, v4
	v_cvt_u32_f32_e32 v4, v4
	v_mul_lo_u32 v1, v3, v4
	v_mul_hi_u32 v1, v4, v1
	v_add_u32_e32 v1, v4, v1
	v_mul_hi_u32 v1, v5, v1
	v_mul_lo_u32 v3, v1, v2
	v_sub_u32_e32 v3, v5, v3
	v_add_u32_e32 v4, 1, v1
	v_cmp_ge_u32_e32 vcc, v3, v2
	s_nop 1
	v_cndmask_b32_e32 v1, v1, v4, vcc
	v_sub_u32_e32 v4, v3, v2
	v_cndmask_b32_e32 v3, v3, v4, vcc
	v_add_u32_e32 v4, 1, v1
	v_cmp_ge_u32_e32 vcc, v3, v2
	v_add_u32_e32 v3, 1, v5
	s_nop 0
	v_cndmask_b32_e32 v1, v1, v4, vcc
	v_mul_lo_u32 v4, v2, v1
	v_add_u32_e32 v2, v4, v2
	v_cmp_ne_u32_e32 vcc, v3, v2
	s_and_saveexec_b64 s[4:5], vcc
	s_xor_b64 s[4:5], exec, s[4:5]
	s_cbranch_execz .LBB0_2546
	s_waitcnt lgkmcnt(0)
	buffer_inv sc1
	v_mov_b32_e32 v0, 0x2000
	global_load_dword v0, v0, s[2:3] offset:1024 sc1
	s_add_u32 s10, s2, 0x2400
	s_addc_u32 s11, s3, 0
	s_waitcnt vmcnt(0)
	v_cmp_eq_u32_e32 vcc, v0, v1
	s_and_saveexec_b64 s[6:7], vcc
	s_cbranch_execz .LBB0_2545
	s_add_u32 s8, s34, 0x101200
	s_addc_u32 s9, s35, 0
	s_mov_b32 s22, 1
	s_mov_b64 s[12:13], 0
	v_mov_b32_e32 v0, 0
	s_branch .LBB0_2536

; __device__ __forceinline__ unsigned xb_ld(unsigned* p)              { return __hip_atomic_load(p, __ATOMIC_RELAXED, __HIP_MEMORY_SCOPE_AGENT); }
; #define XB_SPIN(cond, bar) do { unsigned _sp = 0; while (cond) { __builtin_amdgcn_s_sleep(1); \
;     if ((++_sp & 255u) == 0u) { if (xb_ld(&(bar)[XB_TMO])) break; if (_sp > XB_SPIN_CAP) { atomicAdd(&(bar)[XB_TMO], 1u); break; } } } } while (0)
; __device__ __forceinline__ void xcd_barrier(const XcdBarrier& b) {
;     ...
;             XB_SPIN(xb_ld(&bar[XB_XGEN(b.x)]) == gen, bar);
;             __builtin_amdgcn_fence(__ATOMIC_ACQUIRE, "agent");
;             asm volatile("s_waitcnt vmcnt(0)" ::: "memory");
.LBB0_2545:
	s_or_b64 exec, exec, s[6:7]
	s_waitcnt vmcnt(0)
	s_waitcnt vmcnt(0)
